# grid barrier: first workgroup of an XCD to arrive starts an extra asynchronous L2 write-back while the others finish
# speedup vs baseline: 1.0100x; 1.0010x over previous
; __device__ __forceinline__ unsigned xb_add(unsigned* p, unsigned v) { return __hip_atomic_fetch_add(p, v, __ATOMIC_RELAXED, __HIP_MEMORY_SCOPE_AGENT); }
; __device__ __forceinline__ void xcd_barrier(const XcdBarrier& b) {
;     ...
;         unsigned nloc = b.st[0], nx = b.st[1];
;         if (nloc == 0u) { xcd_barrier_complete(bar, b.x, nloc, nx); b.st[0] = nloc; b.st[1] = nx; }
;         const unsigned old = xb_add(&bar[XB_XSUB(b.x)], 1u);
;         const unsigned gen = old / nloc;
;         if (old + 1u == (gen + 1u) * nloc) {
;             __builtin_amdgcn_fence(__ATOMIC_RELEASE, "agent");
;             asm volatile("s_waitcnt vmcnt(0)" ::: "memory");
;             const unsigned og = xb_add(&bar[XB_TOP], 1u);
;             const unsigned tg = og / nx;
;             if (og + 1u == (tg + 1u) * nx) xb_add(&bar[XB_TOPGEN], 1u);
.LBB0_140:
	s_waitcnt lgkmcnt(0)
	v_readfirstlane_b32 s98, v2
	v_readfirstlane_b32 s99, v0
	v_mov_b32_e32 v1, 0x20008
	ds_read_b32 v5, v1
	s_lshl_b32 s96, s59, 8
	s_add_u32 s96, s54, s96
	s_addc_u32 s97, s55, 0
	v_mov_b32_e32 v3, 0x1000
	v_mov_b32_e32 v4, 1
	global_atomic_add v3, v3, v4, s[96:97] offset:1024 sc0
	s_waitcnt lgkmcnt(0)
	v_readfirstlane_b32 s100, v5
	s_add_i32 s100, s100, 1
	v_mov_b32_e32 v5, v2
	v_mov_b32_e32 v2, s100
	ds_write_b32 v1, v2
	s_mul_i32 s98, s98, s100
	s_mul_i32 s99, s99, s100
	s_waitcnt vmcnt(0)
	v_readfirstlane_b32 s96, v3
	s_add_i32 s96, s96, 1
	s_cmp_lg_u32 s96, s98
	s_cbranch_scc0 .Lmy_bar_last_0
	v_readfirstlane_b32 s97, v5
	s_add_i32 s97, s97, s96
	s_add_i32 s97, s97, -1
	s_cmp_lg_u32 s97, s98
	s_cbranch_scc1 .Lmy_bar_poll_0
	buffer_wbl2 sc1
	s_branch .Lmy_bar_poll_0
.Lmy_bar_last_0:
	buffer_wbl2 sc1
	s_waitcnt vmcnt(0)
	v_mov_b32_e32 v3, 0x3000
	global_atomic_add v3, v4, s[54:55] offset:1024
